# NPD: norm pre-pass xor-1/xor-2 exchanges via DPP quad_perm (16 sites) and prompt-unit epilogue l_run xor-32 via permlane32_swap
# speedup vs baseline: 1.0046x; 1.0046x over previous
; __device__ __forceinline__ void norm_pass(const Args& a, LAS unsigned char* lds, int tid, int lane, int wave) {
;     ...
;         for (int kind = 1; kind < 2; ++kind) { const bf16_t* X = (const bf16_t*)(ws + WS_K); float mx = 0.f;
; #pragma unroll
;             for (int i = 0; i < 8; ++i) { const bf16_t* p = X + (size_t)(b * 64 + wave * 8 + i) * D + lane * 16; const u32x4 w0 = *(const u32x4*)p, w1 = *(const u32x4*)(p + 8); float sq = 0.f;
;                 const unsigned ww[8] = {w0.x, w0.y, w0.z, w0.w, w1.x, w1.y, w1.z, w1.w};
; #pragma unroll
;                 for (int e = 0; e < 8; ++e) { const float lo = __uint_as_float(ww[e] << 16), hi = __uint_as_float(ww[e] & 0xffff0000u); sq += lo * lo + hi * hi; }
;                 sq += __shfl_xor(sq, 1); sq += __shfl_xor(sq, 2); mx = fmaxf(mx, sq); }
;             if ((lane & 3) == 0) red[(wave * 2 + kind) * 16 + (lane >> 2)] = mx; }
.LBB0_339:
	s_add_i32 s6, s4, -7
	s_ashr_i32 s7, s6, 31
	s_lshl_b64 s[6:7], s[6:7], 11
	v_lshl_add_u64 v[0:1], v[8:9], 0, s[6:7]
	s_add_i32 s6, s4, -6
	s_ashr_i32 s7, s6, 31
	global_load_dwordx4 v[16:19], v[0:1], off
	global_load_dwordx4 v[20:23], v[0:1], off offset:16
	s_lshl_b64 s[6:7], s[6:7], 11
	v_lshl_add_u64 v[0:1], v[8:9], 0, s[6:7]
	global_load_dwordx4 v[24:27], v[0:1], off
	global_load_dwordx4 v[28:31], v[0:1], off offset:16
	s_add_i32 s6, s4, -5
	s_add_i32 s12, s4, -4
	s_ashr_i32 s7, s6, 31
	s_ashr_i32 s13, s12, 31
	s_lshl_b64 s[6:7], s[6:7], 11
	s_lshl_b64 s[12:13], s[12:13], 11
	v_lshl_add_u64 v[0:1], v[8:9], 0, s[6:7]
	v_lshl_add_u64 v[4:5], v[8:9], 0, s[12:13]
	global_load_dwordx4 v[32:35], v[0:1], off offset:16
	global_load_dwordx4 v[36:39], v[0:1], off
	s_nop 0
	global_load_dwordx4 v[0:3], v[4:5], off offset:16
	s_nop 0
	global_load_dwordx4 v[4:7], v[4:5], off
	s_add_i32 s6, s4, -3
	s_ashr_i32 s7, s6, 31
	s_lshl_b64 s[6:7], s[6:7], 11
	s_ashr_i32 s5, s4, 31
	s_waitcnt vmcnt(7)
	v_lshlrev_b32_e32 v11, 16, v16
	v_and_b32_e32 v16, 0xffff0000, v16
	v_lshlrev_b32_e32 v40, 16, v17
	v_and_b32_e32 v17, 0xffff0000, v17
	v_lshlrev_b32_e32 v41, 16, v18
	v_and_b32_e32 v18, 0xffff0000, v18
	v_mul_f32_e32 v16, v16, v16
	v_mul_f32_e32 v17, v17, v17
	v_lshlrev_b32_e32 v42, 16, v19
	v_and_b32_e32 v19, 0xffff0000, v19
	s_waitcnt vmcnt(5)
	v_lshlrev_b32_e32 v47, 16, v24
	v_and_b32_e32 v24, 0xffff0000, v24
	v_lshlrev_b32_e32 v48, 16, v25
	v_and_b32_e32 v25, 0xffff0000, v25
	v_mul_f32_e32 v18, v18, v18
	v_fmac_f32_e32 v16, v11, v11
	v_fmac_f32_e32 v17, v40, v40
	v_lshlrev_b32_e32 v43, 16, v20
	v_and_b32_e32 v20, 0xffff0000, v20
	v_lshlrev_b32_e32 v49, 16, v26
	v_and_b32_e32 v26, 0xffff0000, v26
	v_mul_f32_e32 v19, v19, v19
	v_mul_f32_e32 v24, v24, v24
	v_mul_f32_e32 v25, v25, v25
	v_fmac_f32_e32 v18, v41, v41
	v_add_f32_e32 v11, v16, v17
	v_lshlrev_b32_e32 v44, 16, v21
	v_and_b32_e32 v21, 0xffff0000, v21
	v_lshlrev_b32_e32 v50, 16, v27
	v_and_b32_e32 v27, 0xffff0000, v27
	v_mul_f32_e32 v20, v20, v20
	v_mul_f32_e32 v26, v26, v26
	v_fmac_f32_e32 v19, v42, v42
	v_fmac_f32_e32 v24, v47, v47
	v_fmac_f32_e32 v25, v48, v48
	v_add_f32_e32 v11, v18, v11
	v_lshlrev_b32_e32 v45, 16, v22
	v_and_b32_e32 v22, 0xffff0000, v22
	s_waitcnt vmcnt(4)
	v_lshlrev_b32_e32 v51, 16, v28
	v_and_b32_e32 v28, 0xffff0000, v28
	v_mul_f32_e32 v21, v21, v21
	v_mul_f32_e32 v27, v27, v27
	v_fmac_f32_e32 v20, v43, v43
	v_fmac_f32_e32 v26, v49, v49
	v_add_f32_e32 v16, v24, v25
	v_add_f32_e32 v11, v19, v11
	v_lshlrev_b32_e32 v46, 16, v23
	v_and_b32_e32 v23, 0xffff0000, v23
	v_lshlrev_b32_e32 v52, 16, v29
	v_and_b32_e32 v29, 0xffff0000, v29
	v_mul_f32_e32 v22, v22, v22
	v_mul_f32_e32 v28, v28, v28
	v_fmac_f32_e32 v21, v44, v44
	v_fmac_f32_e32 v27, v50, v50
	v_add_f32_e32 v16, v26, v16
	v_add_f32_e32 v11, v20, v11
	v_mul_f32_e32 v23, v23, v23
	v_mul_f32_e32 v29, v29, v29
	v_fmac_f32_e32 v22, v45, v45
	v_fmac_f32_e32 v28, v51, v51
	v_add_f32_e32 v16, v27, v16
	v_add_f32_e32 v11, v21, v11
	s_waitcnt vmcnt(2)
	v_and_b32_e32 v20, 0xffff0000, v36
	v_fmac_f32_e32 v23, v46, v46
	v_fmac_f32_e32 v29, v52, v52
	v_add_f32_e32 v16, v28, v16
	v_add_f32_e32 v11, v22, v11
	v_mul_f32_e32 v28, v20, v20
	v_and_b32_e32 v20, 0xffff0000, v37
	v_lshl_add_u64 v[24:25], v[8:9], 0, s[6:7]
	v_add_f32_e32 v16, v29, v16
	v_add_f32_e32 v11, v23, v11
	v_mul_f32_e32 v29, v20, v20
	global_load_dwordx4 v[20:23], v[24:25], off offset:16
	s_nop 0
	global_load_dwordx4 v[24:27], v[24:25], off
	v_lshlrev_b32_e32 v53, 16, v30
	v_and_b32_e32 v30, 0xffff0000, v30
	v_mul_f32_e32 v18, v30, v30
	v_fmac_f32_e32 v18, v53, v53
	v_and_b32_e32 v19, 0xffff0000, v31
	v_add_f32_e32 v16, v18, v16
	v_lshlrev_b32_e32 v18, 16, v31
	v_mul_f32_e32 v19, v19, v19
	v_fmac_f32_e32 v19, v18, v18
	v_add_f32_e32 v18, v19, v16
	s_nop 1
	v_mov_b32_dpp v17, v11 quad_perm:[1,0,3,2] row_mask:0xf bank_mask:0xf
	s_nop 1
	v_mov_b32_dpp v19, v18 quad_perm:[1,0,3,2] row_mask:0xf bank_mask:0xf
	s_add_i32 s6, s4, -2
	s_ashr_i32 s7, s6, 31
	s_lshl_b64 s[6:7], s[6:7], 11
	s_waitcnt lgkmcnt(1)
	v_add_f32_e32 v11, v11, v17
	s_waitcnt lgkmcnt(0)
	v_add_f32_e32 v17, v18, v19
	v_lshlrev_b32_e32 v19, 16, v36
	v_fmac_f32_e32 v28, v19, v19
	v_lshlrev_b32_e32 v19, 16, v37
	v_fmac_f32_e32 v29, v19, v19
	v_add_f32_e32 v19, v28, v29
	v_and_b32_e32 v29, 0xffff0000, v38
	v_lshlrev_b32_e32 v28, 16, v38
	v_mul_f32_e32 v29, v29, v29
	v_fmac_f32_e32 v29, v28, v28
	v_add_f32_e32 v19, v29, v19
	v_and_b32_e32 v29, 0xffff0000, v39
	v_lshlrev_b32_e32 v28, 16, v39
	v_mul_f32_e32 v29, v29, v29
	v_fmac_f32_e32 v29, v28, v28
	v_add_f32_e32 v19, v29, v19
	v_and_b32_e32 v29, 0xffff0000, v32
	v_lshlrev_b32_e32 v28, 16, v32
	v_mul_f32_e32 v29, v29, v29
	v_fmac_f32_e32 v29, v28, v28
	v_add_f32_e32 v19, v29, v19
	v_and_b32_e32 v29, 0xffff0000, v33
	v_lshlrev_b32_e32 v28, 16, v33
	v_mul_f32_e32 v29, v29, v29
	v_fmac_f32_e32 v29, v28, v28
	v_add_f32_e32 v19, v29, v19
	v_and_b32_e32 v29, 0xffff0000, v34
	v_lshlrev_b32_e32 v28, 16, v34
	v_mul_f32_e32 v29, v29, v29
	v_fmac_f32_e32 v29, v28, v28
	v_add_f32_e32 v19, v29, v19
	v_and_b32_e32 v29, 0xffff0000, v35
	v_lshlrev_b32_e32 v28, 16, v35
	v_mul_f32_e32 v29, v29, v29
	v_fmac_f32_e32 v29, v28, v28
	s_waitcnt vmcnt(2)
; __device__ __forceinline__ void norm_pass(const Args& a, LAS unsigned char* lds, int tid, int lane, int wave) {
;     ...
;         for (int kind = 1; kind < 2; ++kind) { const bf16_t* X = (const bf16_t*)(ws + WS_K); float mx = 0.f;
; #pragma unroll
;             for (int i = 0; i < 8; ++i) { const bf16_t* p = X + (size_t)(b * 64 + wave * 8 + i) * D + lane * 16; const u32x4 w0 = *(const u32x4*)p, w1 = *(const u32x4*)(p + 8); float sq = 0.f;
;                 const unsigned ww[8] = {w0.x, w0.y, w0.z, w0.w, w1.x, w1.y, w1.z, w1.w};
; #pragma unroll
;                 for (int e = 0; e < 8; ++e) { const float lo = __uint_as_float(ww[e] << 16), hi = __uint_as_float(ww[e] & 0xffff0000u); sq += lo * lo + hi * hi; }
;                 sq += __shfl_xor(sq, 1); sq += __shfl_xor(sq, 2); mx = fmaxf(mx, sq); }
;             if ((lane & 3) == 0) red[(wave * 2 + kind) * 16 + (lane >> 2)] = mx; }
	v_lshlrev_b32_e32 v28, 16, v4
	v_and_b32_e32 v4, 0xffff0000, v4
	v_mul_f32_e32 v4, v4, v4
	v_fmac_f32_e32 v4, v28, v28
	v_lshlrev_b32_e32 v28, 16, v5
	v_and_b32_e32 v5, 0xffff0000, v5
	v_mul_f32_e32 v5, v5, v5
	v_fmac_f32_e32 v5, v28, v28
	v_add_f32_e32 v36, v4, v5
	v_and_b32_e32 v5, 0xffff0000, v6
	v_lshlrev_b32_e32 v4, 16, v6
	v_mul_f32_e32 v6, v5, v5
	v_fmac_f32_e32 v6, v4, v4
	v_lshl_add_u64 v[4:5], v[8:9], 0, s[6:7]
	v_add_f32_e32 v19, v29, v19
	global_load_dwordx4 v[28:31], v[4:5], off offset:16
	global_load_dwordx4 v[32:35], v[4:5], off
	v_add_f32_e32 v4, v6, v36
	v_and_b32_e32 v6, 0xffff0000, v7
	v_lshlrev_b32_e32 v5, 16, v7
	v_mul_f32_e32 v6, v6, v6
	v_fmac_f32_e32 v6, v5, v5
	v_lshlrev_b32_e32 v5, 16, v0
	v_and_b32_e32 v0, 0xffff0000, v0
	v_mul_f32_e32 v0, v0, v0
	v_add_f32_e32 v4, v6, v4
	v_fmac_f32_e32 v0, v5, v5
	v_add_f32_e32 v0, v0, v4
	v_lshlrev_b32_e32 v4, 16, v1
	v_and_b32_e32 v1, 0xffff0000, v1
	v_mul_f32_e32 v1, v1, v1
	v_fmac_f32_e32 v1, v4, v4
	v_add_f32_e32 v0, v1, v0
	v_lshlrev_b32_e32 v1, 16, v2
	v_and_b32_e32 v2, 0xffff0000, v2
	v_mul_f32_e32 v2, v2, v2
	v_fmac_f32_e32 v2, v1, v1
	v_add_f32_e32 v0, v2, v0
	v_and_b32_e32 v2, 0xffff0000, v3
	v_lshlrev_b32_e32 v1, 16, v3
	v_mul_f32_e32 v2, v2, v2
	v_fmac_f32_e32 v2, v1, v1
	s_waitcnt vmcnt(2)
	v_and_b32_e32 v1, 0xffff0000, v24
	v_add_f32_e32 v2, v2, v0
	v_lshlrev_b32_e32 v0, 16, v24
	v_mul_f32_e32 v1, v1, v1
	v_and_b32_e32 v4, 0xffff0000, v25
	v_fmac_f32_e32 v1, v0, v0
	v_lshlrev_b32_e32 v0, 16, v25
	v_mul_f32_e32 v4, v4, v4
	s_add_i32 s6, s4, -1
	v_fmac_f32_e32 v4, v0, v0
	v_and_b32_e32 v0, 0xffff0000, v26
	s_ashr_i32 s7, s6, 31
	v_lshlrev_b32_e32 v5, 16, v26
	v_mul_f32_e32 v6, v0, v0
	s_lshl_b64 s[6:7], s[6:7], 11
	v_add_f32_e32 v4, v1, v4
	v_lshl_add_u64 v[0:1], v[8:9], 0, s[6:7]
	v_fmac_f32_e32 v6, v5, v5
	global_load_dwordx4 v[36:39], v[0:1], off offset:16
	global_load_dwordx4 v[40:43], v[0:1], off
	v_add_f32_e32 v0, v6, v4
	v_and_b32_e32 v4, 0xffff0000, v27
	v_lshlrev_b32_e32 v1, 16, v27
	v_mul_f32_e32 v4, v4, v4
	v_fmac_f32_e32 v4, v1, v1
	v_add_f32_e32 v0, v4, v0
	v_and_b32_e32 v4, 0xffff0000, v20
	v_lshlrev_b32_e32 v1, 16, v20
	v_mul_f32_e32 v4, v4, v4
	v_fmac_f32_e32 v4, v1, v1
	v_add_f32_e32 v0, v4, v0
	v_and_b32_e32 v4, 0xffff0000, v21
	v_lshlrev_b32_e32 v1, 16, v21
	v_mul_f32_e32 v4, v4, v4
	v_fmac_f32_e32 v4, v1, v1
	v_add_f32_e32 v0, v4, v0
	v_and_b32_e32 v4, 0xffff0000, v22
	v_lshlrev_b32_e32 v1, 16, v22
	v_mul_f32_e32 v4, v4, v4
	v_fmac_f32_e32 v4, v1, v1
	v_add_f32_e32 v0, v4, v0
	v_and_b32_e32 v4, 0xffff0000, v23
	v_lshlrev_b32_e32 v1, 16, v23
	v_mul_f32_e32 v4, v4, v4
	v_fmac_f32_e32 v4, v1, v1
	v_add_f32_e32 v5, v4, v0
	s_nop 1
	v_mov_b32_dpp v3, v2 quad_perm:[1,0,3,2] row_mask:0xf bank_mask:0xf
	s_nop 1
	v_mov_b32_dpp v6, v5 quad_perm:[1,0,3,2] row_mask:0xf bank_mask:0xf
	s_lshl_b64 s[6:7], s[4:5], 11
	s_nop 1
	v_mov_b32_dpp v44, v19 quad_perm:[1,0,3,2] row_mask:0xf bank_mask:0xf
	s_nop 1
	v_mov_b32_dpp v16, v11 quad_perm:[2,3,0,1] row_mask:0xf bank_mask:0xf
	s_waitcnt lgkmcnt(3)
	v_add_f32_e32 v2, v2, v3
	s_waitcnt lgkmcnt(2)
	v_add_f32_e32 v3, v5, v6
	v_lshl_add_u64 v[6:7], v[8:9], 0, s[6:7]
	global_load_dwordx4 v[20:23], v[6:7], off offset:16
	global_load_dwordx4 v[24:27], v[6:7], off
	s_waitcnt vmcnt(4)
	v_and_b32_e32 v6, 0xffff0000, v32
	s_waitcnt lgkmcnt(1)
	v_add_f32_e32 v0, v19, v44
	v_lshlrev_b32_e32 v19, 16, v32
	v_mul_f32_e32 v6, v6, v6
	v_fmac_f32_e32 v6, v19, v19
	v_and_b32_e32 v19, 0xffff0000, v33
	v_lshlrev_b32_e32 v7, 16, v33
	v_mul_f32_e32 v19, v19, v19
	v_fmac_f32_e32 v19, v7, v7
	v_add_f32_e32 v6, v6, v19
	v_and_b32_e32 v19, 0xffff0000, v34
	v_lshlrev_b32_e32 v7, 16, v34
	v_mul_f32_e32 v19, v19, v19
	v_fmac_f32_e32 v19, v7, v7
	v_add_f32_e32 v6, v19, v6
	v_and_b32_e32 v19, 0xffff0000, v35
	v_lshlrev_b32_e32 v7, 16, v35
	v_mul_f32_e32 v19, v19, v19
	v_fmac_f32_e32 v19, v7, v7
	v_add_f32_e32 v6, v19, v6
	v_and_b32_e32 v19, 0xffff0000, v28
	v_lshlrev_b32_e32 v7, 16, v28
	v_mul_f32_e32 v19, v19, v19
	v_fmac_f32_e32 v19, v7, v7
	v_add_f32_e32 v6, v19, v6
	v_and_b32_e32 v19, 0xffff0000, v29
	v_lshlrev_b32_e32 v7, 16, v29
	v_mul_f32_e32 v19, v19, v19
	v_fmac_f32_e32 v19, v7, v7
	v_add_f32_e32 v6, v19, v6
	v_and_b32_e32 v19, 0xffff0000, v30
	v_lshlrev_b32_e32 v7, 16, v30
	v_mul_f32_e32 v19, v19, v19
	v_fmac_f32_e32 v19, v7, v7
	v_add_f32_e32 v6, v19, v6
	v_and_b32_e32 v19, 0xffff0000, v31
	v_lshlrev_b32_e32 v7, 16, v31
	v_mul_f32_e32 v19, v19, v19
	v_fmac_f32_e32 v19, v7, v7
	v_add_f32_e32 v6, v19, v6
	s_nop 1
	v_mov_b32_dpp v7, v6 quad_perm:[1,0,3,2] row_mask:0xf bank_mask:0xf
	s_nop 1
	v_mov_b32_dpp v18, v17 quad_perm:[2,3,0,1] row_mask:0xf bank_mask:0xf
	s_nop 1
	v_mov_b32_dpp v1, v0 quad_perm:[2,3,0,1] row_mask:0xf bank_mask:0xf
	s_nop 1
	v_mov_b32_dpp v4, v2 quad_perm:[2,3,0,1] row_mask:0xf bank_mask:0xf
	s_waitcnt vmcnt(2)
; __device__ __forceinline__ void norm_pass(const Args& a, LAS unsigned char* lds, int tid, int lane, int wave) {
;     ...
;         for (int kind = 1; kind < 2; ++kind) { const bf16_t* X = (const bf16_t*)(ws + WS_K); float mx = 0.f;
; #pragma unroll
;             for (int i = 0; i < 8; ++i) { const bf16_t* p = X + (size_t)(b * 64 + wave * 8 + i) * D + lane * 16; const u32x4 w0 = *(const u32x4*)p, w1 = *(const u32x4*)(p + 8); float sq = 0.f;
;                 const unsigned ww[8] = {w0.x, w0.y, w0.z, w0.w, w1.x, w1.y, w1.z, w1.w};
; #pragma unroll
;                 for (int e = 0; e < 8; ++e) { const float lo = __uint_as_float(ww[e] << 16), hi = __uint_as_float(ww[e] & 0xffff0000u); sq += lo * lo + hi * hi; }
;                 sq += __shfl_xor(sq, 1); sq += __shfl_xor(sq, 2); mx = fmaxf(mx, sq); }
;             if ((lane & 3) == 0) red[(wave * 2 + kind) * 16 + (lane >> 2)] = mx; }
	v_and_b32_e32 v28, 0xffff0000, v40
	v_lshlrev_b32_e32 v19, 16, v40
	v_mul_f32_e32 v28, v28, v28
	v_and_b32_e32 v29, 0xffff0000, v41
	v_fmac_f32_e32 v28, v19, v19
	v_lshlrev_b32_e32 v19, 16, v41
	v_mul_f32_e32 v29, v29, v29
	v_fmac_f32_e32 v29, v19, v19
	v_add_f32_e32 v19, v28, v29
	v_and_b32_e32 v29, 0xffff0000, v42
	v_lshlrev_b32_e32 v28, 16, v42
	v_mul_f32_e32 v29, v29, v29
	v_fmac_f32_e32 v29, v28, v28
	v_add_f32_e32 v19, v29, v19
	v_and_b32_e32 v29, 0xffff0000, v43
	v_lshlrev_b32_e32 v28, 16, v43
	v_mul_f32_e32 v29, v29, v29
	v_fmac_f32_e32 v29, v28, v28
	v_add_f32_e32 v19, v29, v19
	v_and_b32_e32 v29, 0xffff0000, v36
	v_lshlrev_b32_e32 v28, 16, v36
	v_mul_f32_e32 v29, v29, v29
	v_fmac_f32_e32 v29, v28, v28
	v_add_f32_e32 v19, v29, v19
	v_and_b32_e32 v29, 0xffff0000, v37
	v_lshlrev_b32_e32 v28, 16, v37
	v_mul_f32_e32 v29, v29, v29
	v_fmac_f32_e32 v29, v28, v28
	v_add_f32_e32 v19, v29, v19
	v_and_b32_e32 v29, 0xffff0000, v38
	v_lshlrev_b32_e32 v28, 16, v38
	v_mul_f32_e32 v29, v29, v29
	v_fmac_f32_e32 v29, v28, v28
	v_add_f32_e32 v19, v29, v19
	v_and_b32_e32 v29, 0xffff0000, v39
	v_lshlrev_b32_e32 v28, 16, v39
	v_mul_f32_e32 v29, v29, v29
	v_fmac_f32_e32 v29, v28, v28
	v_add_f32_e32 v28, v29, v19
	s_waitcnt vmcnt(0)
	v_lshlrev_b32_e32 v19, 16, v24
	v_and_b32_e32 v24, 0xffff0000, v24
	v_mul_f32_e32 v24, v24, v24
	v_fmac_f32_e32 v24, v19, v19
	v_lshlrev_b32_e32 v19, 16, v25
	v_and_b32_e32 v25, 0xffff0000, v25
	v_mul_f32_e32 v25, v25, v25
	v_fmac_f32_e32 v25, v19, v19
	v_add_f32_e32 v19, v24, v25
	v_and_b32_e32 v25, 0xffff0000, v26
	v_lshlrev_b32_e32 v24, 16, v26
	v_mul_f32_e32 v25, v25, v25
	v_fmac_f32_e32 v25, v24, v24
	v_add_f32_e32 v19, v25, v19
	v_and_b32_e32 v25, 0xffff0000, v27
	v_lshlrev_b32_e32 v24, 16, v27
	v_mul_f32_e32 v25, v25, v25
	v_fmac_f32_e32 v25, v24, v24
	v_lshlrev_b32_e32 v24, 16, v20
	v_and_b32_e32 v20, 0xffff0000, v20
	v_mul_f32_e32 v20, v20, v20
	v_add_f32_e32 v19, v25, v19
	v_fmac_f32_e32 v20, v24, v24
	v_add_f32_e32 v19, v20, v19
	v_lshlrev_b32_e32 v20, 16, v21
	v_and_b32_e32 v21, 0xffff0000, v21
	v_mul_f32_e32 v21, v21, v21
	v_fmac_f32_e32 v21, v20, v20
	v_add_f32_e32 v19, v21, v19
	v_and_b32_e32 v21, 0xffff0000, v22
	v_lshlrev_b32_e32 v20, 16, v22
	v_mul_f32_e32 v21, v21, v21
	v_fmac_f32_e32 v21, v20, v20
	v_add_f32_e32 v19, v21, v19
	v_and_b32_e32 v21, 0xffff0000, v23
	v_lshlrev_b32_e32 v20, 16, v23
	v_mul_f32_e32 v21, v21, v21
	v_fmac_f32_e32 v21, v20, v20
	v_add_f32_e32 v21, v21, v19
	s_nop 1
	v_mov_b32_dpp v29, v28 quad_perm:[1,0,3,2] row_mask:0xf bank_mask:0xf
	s_nop 1
	v_mov_b32_dpp v22, v21 quad_perm:[1,0,3,2] row_mask:0xf bank_mask:0xf
	s_waitcnt lgkmcnt(5)
	v_add_f32_e32 v6, v6, v7
	s_nop 1
	v_mov_b32_dpp v5, v3 quad_perm:[2,3,0,1] row_mask:0xf bank_mask:0xf
	s_nop 1
	v_mov_b32_dpp v19, v6 quad_perm:[2,3,0,1] row_mask:0xf bank_mask:0xf
	s_waitcnt lgkmcnt(3)
	v_add_f32_e32 v7, v28, v29
	s_waitcnt lgkmcnt(2)
	v_add_f32_e32 v21, v21, v22
	s_nop 1
	v_mov_b32_dpp v20, v7 quad_perm:[2,3,0,1] row_mask:0xf bank_mask:0xf
	s_nop 1
	v_mov_b32_dpp v22, v21 quad_perm:[2,3,0,1] row_mask:0xf bank_mask:0xf
	s_and_saveexec_b64 s[6:7], vcc
	s_cbranch_execz .LBB0_341
	v_add_f32_e32 v11, v11, v16
	v_add_f32_e32 v16, v17, v18
	v_max3_f32 v11, v11, 0, v16
	v_add_f32_e32 v0, v0, v1
	v_add_f32_e32 v1, v2, v4
	v_max3_f32 v0, v11, v0, v1
	s_waitcnt lgkmcnt(3)
	v_add_f32_e32 v1, v3, v5
	s_waitcnt lgkmcnt(2)
	v_add_f32_e32 v2, v6, v19
	v_max3_f32 v0, v0, v1, v2
	s_waitcnt lgkmcnt(1)
	v_add_f32_e32 v1, v7, v20
	s_waitcnt lgkmcnt(0)
	v_add_f32_e32 v2, v21, v22
	v_max3_f32 v0, v0, v1, v2
	ds_write_b32 v15, v0 offset:64

; __device__ __forceinline__ unsigned cvt_pk_bf16(float lo, float hi) { unsigned r; asm volatile("v_cvt_pk_bf16_f32 %0, %1, %2" : "=v"(r) : "v"(lo), "v"(hi)); return r; }
; __device__ __forceinline__ void attn_unit(const Args& a, LAS unsigned char* lds, const int mode, const int h, const int qb, const int tid_in, const int lane_in, const int wave) {
;     ...
;     if (active) {
;         const float lt = l_run + __shfl_xor(l_run, 32); const float rl = 1.0f / lt;
;         bf16_t* Y = (bf16_t*)(ws + WS_YCAT) + (size_t)qrow * (2 * D) + D + h * HD;
; #pragma unroll
;         for (int g = 0; g < 4; ++g) {
;             u32x2 w0, w1; w0.x = cvt_pk_bf16(o0[4 * g] * rl, o0[4 * g + 1] * rl); w0.y = cvt_pk_bf16(o0[4 * g + 2] * rl, o0[4 * g + 3] * rl);
;             w1.x = cvt_pk_bf16(o1[4 * g] * rl, o1[4 * g + 1] * rl); w1.y = cvt_pk_bf16(o1[4 * g + 2] * rl, o1[4 * g + 3] * rl);
;             *(u32x2*)(Y + 8 * g + 4 * hi) = w0; *(u32x2*)(Y + 32 + 8 * g + 4 * hi) = w1; }
;     }
.LBB0_540:
	v_readlane_b32 s0, v254, 23
	v_readlane_b32 s1, v254, 24
	s_and_b64 vcc, exec, s[0:1]
	s_cbranch_vccz .LBB0_542
	v_and_b32_e32 v34, 64, v138
	v_xor_b32_e32 v1, 32, v138
	v_add_u32_e32 v34, 64, v34
	v_cmp_lt_i32_e32 vcc, v1, v34
	v_lshlrev_b64 v[34:35], 12, v[92:93]
	v_lshl_add_u64 v[34:35], s[88:89], 0, v[34:35]
	v_cndmask_b32_e32 v1, v138, v1, vcc
	v_lshlrev_b32_e32 v1, 2, v1
	v_cmp_gt_u32_e32 vcc, 32, v138
	v_mov_b32_e32 v1, v103
	v_mov_b32_e32 v253, v103
	s_nop 1
	v_permlane32_swap_b32_e32 v1, v253
	v_cndmask_b32_e64 v1, v1, v253, vcc
	s_lshl_b32 s72, s14, 1
	v_lshl_add_u64 v[34:35], v[34:35], 0, s[72:73]
	v_mov_b32_e32 v91, v0
	v_lshl_add_u64 v[34:35], v[34:35], 0, v[90:91]
	s_waitcnt lgkmcnt(0)
	v_add_f32_e32 v1, v103, v1
	v_div_scale_f32 v36, s[0:1], v1, v1, 1.0
	v_rcp_f32_e32 v37, v36
	v_div_scale_f32 v38, vcc, 1.0, v1, 1.0
	s_mov_b64 s[0:1], 0x14000800
	v_fma_f32 v39, -v36, v37, 1.0
	v_fmac_f32_e32 v37, v39, v37
	v_mul_f32_e32 v39, v38, v37
	v_fma_f32 v40, -v36, v39, v38
	v_fmac_f32_e32 v39, v40, v37
	v_fma_f32 v36, -v36, v39, v38
	v_div_fmas_f32 v36, v36, v37, v39
	v_div_fixup_f32 v1, v36, v1, 1.0
	v_mul_f32_e32 v18, v18, v1
	v_mul_f32_e32 v19, v19, v1
	v_cvt_pk_bf16_f32 v18, v18, v19
	v_mul_f32_e32 v19, v20, v1
	v_mul_f32_e32 v2, v2, v1
	v_mul_f32_e32 v3, v3, v1
	v_lshl_add_u64 v[36:37], v[34:35], 0, s[0:1]
	v_mul_f32_e32 v20, v21, v1
	v_cvt_pk_bf16_f32 v19, v19, v20
	v_cvt_pk_bf16_f32 v2, v2, v3
	v_mul_f32_e32 v3, v4, v1
	v_mul_f32_e32 v4, v5, v1
	s_brev_b32 s0, 40
	v_cvt_pk_bf16_f32 v3, v3, v4
	v_add_co_u32_e32 v4, vcc, s0, v34
	s_nop 1
	v_addc_co_u32_e32 v5, vcc, 0, v35, vcc
	global_store_dwordx2 v[4:5], v[18:19], off offset:2048
	global_store_dwordx2 v[36:37], v[2:3], off offset:64
	v_mul_f32_e32 v2, v22, v1
	v_mul_f32_e32 v3, v23, v1
	v_cvt_pk_bf16_f32 v2, v2, v3
	v_mul_f32_e32 v3, v24, v1
	v_mul_f32_e32 v4, v25, v1
	v_cvt_pk_bf16_f32 v3, v3, v4
	v_mul_f32_e32 v4, v6, v1
	v_mul_f32_e32 v5, v7, v1
	v_cvt_pk_bf16_f32 v4, v4, v5
	v_mul_f32_e32 v5, v8, v1
	v_mul_f32_e32 v6, v9, v1
	v_cvt_pk_bf16_f32 v5, v5, v6
	global_store_dwordx2 v[36:37], v[2:3], off offset:16
	global_store_dwordx2 v[36:37], v[4:5], off offset:80
	v_mul_f32_e32 v2, v26, v1
	v_mul_f32_e32 v3, v27, v1
	v_cvt_pk_bf16_f32 v2, v2, v3
	v_mul_f32_e32 v3, v28, v1
	v_mul_f32_e32 v4, v29, v1
	v_cvt_pk_bf16_f32 v3, v3, v4
	v_mul_f32_e32 v4, v10, v1
	v_mul_f32_e32 v5, v11, v1
	v_cvt_pk_bf16_f32 v4, v4, v5
	v_mul_f32_e32 v5, v12, v1
	v_mul_f32_e32 v6, v13, v1
	v_cvt_pk_bf16_f32 v5, v5, v6
	global_store_dwordx2 v[36:37], v[2:3], off offset:32
	global_store_dwordx2 v[36:37], v[4:5], off offset:96
	v_mul_f32_e32 v2, v30, v1
	v_mul_f32_e32 v3, v31, v1
	v_cvt_pk_bf16_f32 v2, v2, v3
	v_mul_f32_e32 v3, v32, v1
	v_mul_f32_e32 v4, v33, v1
	v_cvt_pk_bf16_f32 v3, v3, v4
	v_mul_f32_e32 v4, v14, v1
	v_mul_f32_e32 v5, v15, v1
	v_cvt_pk_bf16_f32 v4, v4, v5
	v_mul_f32_e32 v5, v16, v1
	v_mul_f32_e32 v1, v17, v1
	v_cvt_pk_bf16_f32 v5, v5, v1
	global_store_dwordx2 v[36:37], v[2:3], off offset:48
	global_store_dwordx2 v[36:37], v[4:5], off offset:112
	s_cbranch_execnz .LBB0_397
	s_branch .LBB0_543
